# adds: nt cache policy on the mLSTM output-pass stores
# speedup vs baseline: 1.0104x; 1.0104x over previous
; #define LAS __attribute__((address_space(3)))
; DI unsigned pk2(float lo, float hi) { f32x2n v = {lo, hi}; bf16x2n b = __builtin_convertvector(v, bf16x2n); return __builtin_bit_cast(unsigned, b); }
; DI float frsq(float x) { return __builtin_amdgcn_rsqf(x); }
; template <bool P2>
; DI void ml_pass(LAS unsigned char* lds, const bf16_t* PROJ, const float* GATES, float* STATE, float* SC, bf16_t* YM,
;                 const float* convw, const float* convb, const float* ogain, int G, int bid) {
;     ...
;                 for (int it = 0; it < 4; ++it) { const int idx = tid + 512 * it, t = idx >> 5, pc3 = idx & 31;
;                     float ssum = 0.f;
; #pragma unroll
;                     for (int ww = 0; ww < 8; ++ww) ssum += ssq[ww * 64 + t];
;                     const float rstd = frsq(ssum * (1.0f / 256.0f) + EPS);
;                     const u32x4 hv = *(const LAS u32x4*)(OUTs + t * 264 + 8 * pc3);
;                     const u32x4 op = *(const u32x4*)(PROJ + (row0 + t) * 3072 + 2048 + 256 * h + 8 * pc3);
;                     const f32x4 g0 = *(const f32x4*)(ogain + h * 256 + 8 * pc3), g1 = *(const f32x4*)(ogain + h * 256 + 8 * pc3 + 4);
;                     float hvf[8] = {bflo(hv.x), bfhi(hv.x), bflo(hv.y), bfhi(hv.y), bflo(hv.z), bfhi(hv.z), bflo(hv.w), bfhi(hv.w)};
;                     float opf[8] = {bflo(op.x), bfhi(op.x), bflo(op.y), bfhi(op.y), bflo(op.z), bfhi(op.z), bflo(op.w), bfhi(op.w)};
;                     float y[8];
; #pragma unroll
;                     for (int j = 0; j < 8; ++j) y[j] = hvf[j] * rstd * (j < 4 ? g0[j & 3] : g1[j & 3]) * opf[j];
;                     u32x4 o; o.x = pk2(y[0], y[1]); o.y = pk2(y[2], y[3]); o.z = pk2(y[4], y[5]); o.w = pk2(y[6], y[7]);
;                     *(u32x4*)(YM + (row0 + t) * 1024 + 256 * h + 8 * pc3) = o; }
.LBB0_133:
	s_or_b64 exec, exec, s[0:1]
	v_lshlrev_b32_e32 v64, 3, v133
	v_and_b32_e32 v64, 0xf8, v64
	s_add_i32 s0, 0, 0x18400
	v_lshlrev_b32_e32 v112, 1, v64
	v_add_u32_e32 v70, s0, v112
	v_ashrrev_i32_e32 v72, 5, v133
	s_add_i32 s0, 0, 0x20e00
	s_waitcnt lgkmcnt(0)
	s_barrier
	v_lshl_add_u32 v66, v72, 2, s0
	v_lshlrev_b32_e32 v71, 2, v64
	ds_read2st64_b32 v[64:65], v66 offset1:1
	v_ashrrev_i32_e32 v73, 31, v72
	v_lshl_add_u64 v[88:89], s[60:61], 0, v[72:73]
	s_mov_b32 s47, s35
	v_lshl_add_u64 v[68:69], s[58:59], 0, v[112:113]
	s_waitcnt lgkmcnt(0)
	v_add_f32_e32 v64, 0, v64
	v_add_f32_e32 v67, v64, v65
	ds_read2st64_b32 v[64:65], v66 offset0:2 offset1:3
	s_add_i32 s76, s76, 1
	s_cmp_eq_u32 s76, 8
	s_waitcnt lgkmcnt(0)
	v_add_f32_e32 v64, v67, v64
	v_add_f32_e32 v67, v64, v65
	ds_read2st64_b32 v[64:65], v66 offset0:4 offset1:5
	s_waitcnt lgkmcnt(0)
	v_add_f32_e32 v64, v67, v64
	v_add_f32_e32 v67, v64, v65
	ds_read2st64_b32 v[64:65], v66 offset0:6 offset1:7
	s_waitcnt lgkmcnt(0)
	v_add_f32_e32 v64, v67, v64
	v_add_f32_e32 v64, v64, v65
	v_fmamk_f32 v64, v64, 0x3b800000, v229
	v_rsq_f32_e32 v86, v64
	v_mad_u64_u32 v[64:65], s[48:49], v72, s81, v[70:71]
	v_mov_b64_e32 v[72:73], s[28:29]
	v_mad_u64_u32 v[74:75], s[48:49], v88, s79, v[72:73]
	v_mad_i32_i24 v75, v89, s79, v75
	v_lshl_add_u64 v[74:75], v[74:75], 0, s[46:47]
	v_lshl_add_u64 v[74:75], v[74:75], 0, v[112:113]
	v_add_co_u32_e32 v74, vcc, s37, v74
	ds_read_b128 v[64:67], v64
	s_nop 0
	v_addc_co_u32_e32 v75, vcc, 0, v75, vcc
	global_load_dwordx4 v[74:77], v[74:75], off
	s_nop 0
	global_load_dwordx4 v[78:81], v71, s[56:57] offset:16
	global_load_dwordx4 v[82:85], v71, s[56:57]
	s_waitcnt lgkmcnt(0)
	v_lshlrev_b32_e32 v90, 16, v64
	v_and_b32_e32 v91, 0xffff0000, v64
	v_lshlrev_b32_e32 v64, 16, v65
	v_and_b32_e32 v65, 0xffff0000, v65
	v_pk_mul_f32 v[64:65], v[86:87], v[64:65] op_sel_hi:[0,1]
	v_pk_mul_f32 v[90:91], v[86:87], v[90:91] op_sel_hi:[0,1]
	s_waitcnt vmcnt(2)
	v_lshlrev_b32_e32 v92, 16, v74
	v_and_b32_e32 v93, 0xffff0000, v74
	v_lshlrev_b32_e32 v74, 16, v75
	v_and_b32_e32 v75, 0xffff0000, v75
	s_waitcnt vmcnt(0)
	v_pk_mul_f32 v[64:65], v[84:85], v[64:65]
	v_lshlrev_b32_e32 v84, 16, v76
	v_pk_mul_f32 v[74:75], v[64:65], v[74:75]
	v_lshlrev_b32_e32 v64, 16, v66
	v_and_b32_e32 v65, 0xffff0000, v66
	v_pk_mul_f32 v[64:65], v[86:87], v[64:65] op_sel_hi:[0,1]
	v_and_b32_e32 v85, 0xffff0000, v76
	v_pk_mul_f32 v[64:65], v[64:65], v[78:79]
	v_pk_mul_f32 v[82:83], v[82:83], v[90:91]
	v_pk_mul_f32 v[78:79], v[64:65], v[84:85]
	v_lshlrev_b32_e32 v64, 16, v67
	v_and_b32_e32 v65, 0xffff0000, v67
	v_pk_mul_f32 v[64:65], v[86:87], v[64:65] op_sel_hi:[0,1]
	v_lshlrev_b32_e32 v66, 16, v77
	v_and_b32_e32 v67, 0xffff0000, v77
	v_pk_mul_f32 v[64:65], v[64:65], v[80:81]
	v_pk_mul_f32 v[82:83], v[82:83], v[92:93]
	v_pk_mul_f32 v[76:77], v[64:65], v[66:67]
	v_cvt_pk_bf16_f32 v65, v74, v75
	v_lshlrev_b64 v[74:75], 11, v[88:89]
	v_cvt_pk_bf16_f32 v64, v82, v83
	v_cvt_pk_bf16_f32 v66, v78, v79
	v_cvt_pk_bf16_f32 v67, v76, v77
	v_lshl_add_u64 v[74:75], v[68:69], 0, v[74:75]
	global_store_dwordx4 v[74:75], v[64:67], off nt
	s_nop 1
	v_add_u32_e32 v64, 0x200, v133
	v_ashrrev_i32_e32 v76, 5, v64
	v_lshl_add_u32 v66, v76, 2, s0
	ds_read2st64_b32 v[64:65], v66 offset1:1
	v_ashrrev_i32_e32 v77, 31, v76
	v_lshl_add_u64 v[88:89], s[60:61], 0, v[76:77]
	s_waitcnt lgkmcnt(0)
	v_add_f32_e32 v64, 0, v64
	v_add_f32_e32 v67, v64, v65
	ds_read2st64_b32 v[64:65], v66 offset0:2 offset1:3
	s_waitcnt lgkmcnt(0)
	v_add_f32_e32 v64, v67, v64
	v_add_f32_e32 v67, v64, v65
	ds_read2st64_b32 v[64:65], v66 offset0:4 offset1:5
	s_waitcnt lgkmcnt(0)
	v_add_f32_e32 v64, v67, v64
	v_add_f32_e32 v67, v64, v65
	ds_read2st64_b32 v[64:65], v66 offset0:6 offset1:7
	s_waitcnt lgkmcnt(0)
	v_add_f32_e32 v64, v67, v64
	v_add_f32_e32 v64, v64, v65
	v_fmamk_f32 v64, v64, 0x3b800000, v229
	v_rsq_f32_e32 v74, v64
	v_mad_u64_u32 v[64:65], s[48:49], v76, s81, v[70:71]
	v_mad_u64_u32 v[76:77], s[48:49], v88, s79, v[72:73]
	v_mad_i32_i24 v77, v89, s79, v77
	v_lshl_add_u64 v[76:77], v[76:77], 0, s[46:47]
	v_lshl_add_u64 v[76:77], v[76:77], 0, v[112:113]
	v_add_co_u32_e32 v76, vcc, s37, v76
	ds_read_b128 v[64:67], v64
	s_nop 0
	v_addc_co_u32_e32 v77, vcc, 0, v77, vcc
	global_load_dwordx4 v[76:79], v[76:77], off
	s_nop 0
	global_load_dwordx4 v[80:83], v71, s[56:57] offset:16
	global_load_dwordx4 v[84:87], v71, s[56:57]
	s_waitcnt lgkmcnt(0)
	v_lshlrev_b32_e32 v90, 16, v64
	v_and_b32_e32 v91, 0xffff0000, v64
	v_lshlrev_b32_e32 v64, 16, v65
	v_and_b32_e32 v65, 0xffff0000, v65
	v_pk_mul_f32 v[64:65], v[74:75], v[64:65] op_sel_hi:[0,1]
	v_pk_mul_f32 v[90:91], v[74:75], v[90:91] op_sel_hi:[0,1]
	s_waitcnt vmcnt(2)
	v_lshlrev_b32_e32 v92, 16, v76
	v_and_b32_e32 v93, 0xffff0000, v76
	v_lshlrev_b32_e32 v76, 16, v77
	v_and_b32_e32 v77, 0xffff0000, v77
	s_waitcnt vmcnt(0)
	v_pk_mul_f32 v[64:65], v[86:87], v[64:65]
	v_lshlrev_b32_e32 v86, 16, v78
	v_pk_mul_f32 v[76:77], v[64:65], v[76:77]
	v_lshlrev_b32_e32 v64, 16, v66
	v_and_b32_e32 v65, 0xffff0000, v66
	v_pk_mul_f32 v[64:65], v[74:75], v[64:65] op_sel_hi:[0,1]
	v_and_b32_e32 v87, 0xffff0000, v78
	v_pk_mul_f32 v[64:65], v[64:65], v[80:81]
	v_lshlrev_b32_e32 v66, 16, v79
	v_pk_mul_f32 v[80:81], v[64:65], v[86:87]
	v_lshlrev_b32_e32 v64, 16, v67
	v_and_b32_e32 v65, 0xffff0000, v67
	v_pk_mul_f32 v[64:65], v[74:75], v[64:65] op_sel_hi:[0,1]
	v_and_b32_e32 v67, 0xffff0000, v79
	v_pk_mul_f32 v[64:65], v[64:65], v[82:83]
	v_pk_mul_f32 v[84:85], v[84:85], v[90:91]
	v_pk_mul_f32 v[74:75], v[64:65], v[66:67]
	v_pk_mul_f32 v[84:85], v[84:85], v[92:93]
	v_cvt_pk_bf16_f32 v67, v74, v75
	v_lshlrev_b64 v[74:75], 11, v[88:89]
	v_cvt_pk_bf16_f32 v64, v84, v85
	v_cvt_pk_bf16_f32 v65, v76, v77
	v_cvt_pk_bf16_f32 v66, v80, v81
	v_lshl_add_u64 v[74:75], v[68:69], 0, v[74:75]
	global_store_dwordx4 v[74:75], v[64:67], off nt
	s_nop 1
	v_add_u32_e32 v64, 0x400, v133
	v_ashrrev_i32_e32 v76, 5, v64
	v_lshl_add_u32 v66, v76, 2, s0
	ds_read2st64_b32 v[64:65], v66 offset1:1
	v_ashrrev_i32_e32 v77, 31, v76
	v_lshl_add_u64 v[88:89], s[60:61], 0, v[76:77]
	s_waitcnt lgkmcnt(0)
; #define LAS __attribute__((address_space(3)))
; DI unsigned pk2(float lo, float hi) { f32x2n v = {lo, hi}; bf16x2n b = __builtin_convertvector(v, bf16x2n); return __builtin_bit_cast(unsigned, b); }
; DI float frsq(float x) { return __builtin_amdgcn_rsqf(x); }
; template <bool P2>
; DI void ml_pass(LAS unsigned char* lds, const bf16_t* PROJ, const float* GATES, float* STATE, float* SC, bf16_t* YM,
;                 const float* convw, const float* convb, const float* ogain, int G, int bid) {
;     ...
;                 for (int it = 0; it < 4; ++it) { const int idx = tid + 512 * it, t = idx >> 5, pc3 = idx & 31;
;                     float ssum = 0.f;
; #pragma unroll
;                     for (int ww = 0; ww < 8; ++ww) ssum += ssq[ww * 64 + t];
;                     const float rstd = frsq(ssum * (1.0f / 256.0f) + EPS);
;                     const u32x4 hv = *(const LAS u32x4*)(OUTs + t * 264 + 8 * pc3);
;                     const u32x4 op = *(const u32x4*)(PROJ + (row0 + t) * 3072 + 2048 + 256 * h + 8 * pc3);
;                     const f32x4 g0 = *(const f32x4*)(ogain + h * 256 + 8 * pc3), g1 = *(const f32x4*)(ogain + h * 256 + 8 * pc3 + 4);
;                     float hvf[8] = {bflo(hv.x), bfhi(hv.x), bflo(hv.y), bfhi(hv.y), bflo(hv.z), bfhi(hv.z), bflo(hv.w), bfhi(hv.w)};
;                     float opf[8] = {bflo(op.x), bfhi(op.x), bflo(op.y), bfhi(op.y), bflo(op.z), bfhi(op.z), bflo(op.w), bfhi(op.w)};
;                     float y[8];
; #pragma unroll
;                     for (int j = 0; j < 8; ++j) y[j] = hvf[j] * rstd * (j < 4 ? g0[j & 3] : g1[j & 3]) * opf[j];
;                     u32x4 o; o.x = pk2(y[0], y[1]); o.y = pk2(y[2], y[3]); o.z = pk2(y[4], y[5]); o.w = pk2(y[6], y[7]);
;                     *(u32x4*)(YM + (row0 + t) * 1024 + 256 * h + 8 * pc3) = o; }
	v_add_f32_e32 v64, 0, v64
	v_add_f32_e32 v67, v64, v65
	ds_read2st64_b32 v[64:65], v66 offset0:2 offset1:3
	s_waitcnt lgkmcnt(0)
	v_add_f32_e32 v64, v67, v64
	v_add_f32_e32 v67, v64, v65
	ds_read2st64_b32 v[64:65], v66 offset0:4 offset1:5
	s_waitcnt lgkmcnt(0)
	v_add_f32_e32 v64, v67, v64
	v_add_f32_e32 v67, v64, v65
	ds_read2st64_b32 v[64:65], v66 offset0:6 offset1:7
	s_waitcnt lgkmcnt(0)
	v_add_f32_e32 v64, v67, v64
	v_add_f32_e32 v64, v64, v65
	v_fmamk_f32 v64, v64, 0x3b800000, v229
	v_rsq_f32_e32 v74, v64
	v_mad_u64_u32 v[64:65], s[48:49], v76, s81, v[70:71]
	v_mad_u64_u32 v[76:77], s[48:49], v88, s79, v[72:73]
	v_mad_i32_i24 v77, v89, s79, v77
	v_lshl_add_u64 v[76:77], v[76:77], 0, s[46:47]
	v_lshl_add_u64 v[76:77], v[76:77], 0, v[112:113]
	v_add_co_u32_e32 v76, vcc, s37, v76
	ds_read_b128 v[64:67], v64
	s_nop 0
	v_addc_co_u32_e32 v77, vcc, 0, v77, vcc
	global_load_dwordx4 v[76:79], v[76:77], off
	s_nop 0
	global_load_dwordx4 v[80:83], v71, s[56:57] offset:16
	global_load_dwordx4 v[84:87], v71, s[56:57]
	s_waitcnt lgkmcnt(0)
	v_lshlrev_b32_e32 v90, 16, v64
	v_and_b32_e32 v91, 0xffff0000, v64
	v_lshlrev_b32_e32 v64, 16, v65
	v_and_b32_e32 v65, 0xffff0000, v65
	v_pk_mul_f32 v[64:65], v[74:75], v[64:65] op_sel_hi:[0,1]
	v_pk_mul_f32 v[90:91], v[74:75], v[90:91] op_sel_hi:[0,1]
	s_waitcnt vmcnt(2)
	v_lshlrev_b32_e32 v92, 16, v76
	v_and_b32_e32 v93, 0xffff0000, v76
	v_lshlrev_b32_e32 v76, 16, v77
	v_and_b32_e32 v77, 0xffff0000, v77
	s_waitcnt vmcnt(0)
	v_pk_mul_f32 v[64:65], v[86:87], v[64:65]
	v_lshlrev_b32_e32 v86, 16, v78
	v_pk_mul_f32 v[76:77], v[64:65], v[76:77]
	v_lshlrev_b32_e32 v64, 16, v66
	v_and_b32_e32 v65, 0xffff0000, v66
	v_pk_mul_f32 v[64:65], v[74:75], v[64:65] op_sel_hi:[0,1]
	v_and_b32_e32 v87, 0xffff0000, v78
	v_pk_mul_f32 v[64:65], v[64:65], v[80:81]
	v_lshlrev_b32_e32 v66, 16, v79
	v_pk_mul_f32 v[80:81], v[64:65], v[86:87]
	v_lshlrev_b32_e32 v64, 16, v67
	v_and_b32_e32 v65, 0xffff0000, v67
	v_pk_mul_f32 v[64:65], v[74:75], v[64:65] op_sel_hi:[0,1]
	v_and_b32_e32 v67, 0xffff0000, v79
	v_pk_mul_f32 v[64:65], v[64:65], v[82:83]
	v_pk_mul_f32 v[84:85], v[84:85], v[90:91]
	v_pk_mul_f32 v[74:75], v[64:65], v[66:67]
	v_pk_mul_f32 v[84:85], v[84:85], v[92:93]
	v_cvt_pk_bf16_f32 v67, v74, v75
	v_lshlrev_b64 v[74:75], 11, v[88:89]
	v_cvt_pk_bf16_f32 v64, v84, v85
	v_cvt_pk_bf16_f32 v65, v76, v77
	v_cvt_pk_bf16_f32 v66, v80, v81
	v_lshl_add_u64 v[74:75], v[68:69], 0, v[74:75]
	global_store_dwordx4 v[74:75], v[64:67], off nt
	s_nop 1
	v_add_u32_e32 v64, 0x600, v133
	v_ashrrev_i32_e32 v76, 5, v64
	v_lshl_add_u32 v66, v76, 2, s0
	ds_read2st64_b32 v[64:65], v66 offset1:1
	v_ashrrev_i32_e32 v77, 31, v76
	v_lshl_add_u64 v[84:85], s[60:61], 0, v[76:77]
	v_mad_u64_u32 v[72:73], s[0:1], v84, s79, v[72:73]
	s_waitcnt lgkmcnt(0)
	v_add_f32_e32 v64, 0, v64
	v_add_f32_e32 v67, v64, v65
	ds_read2st64_b32 v[64:65], v66 offset0:2 offset1:3
	v_mad_i32_i24 v73, v85, s79, v73
	v_lshl_add_u64 v[72:73], v[72:73], 0, s[46:47]
	v_lshl_add_u64 v[72:73], v[72:73], 0, v[112:113]
	v_add_co_u32_e32 v72, vcc, s37, v72
	s_waitcnt lgkmcnt(0)
	v_add_f32_e32 v64, v67, v64
	v_add_f32_e32 v67, v64, v65
	ds_read2st64_b32 v[64:65], v66 offset0:4 offset1:5
	v_addc_co_u32_e32 v73, vcc, 0, v73, vcc
	v_mov_b32_e32 v112, v132
	s_waitcnt lgkmcnt(0)
	v_add_f32_e32 v64, v67, v64
	v_add_f32_e32 v67, v64, v65
	ds_read2st64_b32 v[64:65], v66 offset0:6 offset1:7
	s_waitcnt lgkmcnt(0)
	v_add_f32_e32 v64, v67, v64
	v_add_f32_e32 v64, v64, v65
	v_fmamk_f32 v64, v64, 0x3b800000, v229
	v_rsq_f32_e32 v74, v64
	v_mad_u64_u32 v[64:65], s[0:1], v76, s81, v[70:71]
	ds_read_b128 v[64:67], v64
	global_load_dwordx4 v[76:79], v[72:73], off
	global_load_dwordx4 v[80:83], v71, s[56:57] offset:16
	s_nop 0
	global_load_dwordx4 v[70:73], v71, s[56:57]
	s_waitcnt lgkmcnt(0)
	v_lshlrev_b32_e32 v86, 16, v64
	v_and_b32_e32 v87, 0xffff0000, v64
	v_lshlrev_b32_e32 v64, 16, v65
	v_and_b32_e32 v65, 0xffff0000, v65
	v_pk_mul_f32 v[64:65], v[74:75], v[64:65] op_sel_hi:[0,1]
	v_pk_mul_f32 v[86:87], v[74:75], v[86:87] op_sel_hi:[0,1]
	s_waitcnt vmcnt(2)
	v_lshlrev_b32_e32 v88, 16, v76
	v_and_b32_e32 v89, 0xffff0000, v76
	v_lshlrev_b32_e32 v76, 16, v77
	v_and_b32_e32 v77, 0xffff0000, v77
	s_waitcnt vmcnt(0)
	v_pk_mul_f32 v[64:65], v[72:73], v[64:65]
	v_pk_mul_f32 v[70:71], v[70:71], v[86:87]
	v_pk_mul_f32 v[72:73], v[64:65], v[76:77]
	v_lshlrev_b32_e32 v64, 16, v66
	v_and_b32_e32 v65, 0xffff0000, v66
	v_pk_mul_f32 v[64:65], v[74:75], v[64:65] op_sel_hi:[0,1]
	v_lshlrev_b32_e32 v76, 16, v78
	v_and_b32_e32 v77, 0xffff0000, v78
	v_pk_mul_f32 v[64:65], v[64:65], v[80:81]
	v_pk_mul_f32 v[70:71], v[70:71], v[88:89]
	v_pk_mul_f32 v[76:77], v[64:65], v[76:77]
	v_lshlrev_b32_e32 v64, 16, v67
	v_and_b32_e32 v65, 0xffff0000, v67
	v_pk_mul_f32 v[64:65], v[74:75], v[64:65] op_sel_hi:[0,1]
	v_lshlrev_b32_e32 v66, 16, v79
	v_and_b32_e32 v67, 0xffff0000, v79
	v_pk_mul_f32 v[64:65], v[64:65], v[82:83]
	s_nop 0
	v_pk_mul_f32 v[74:75], v[64:65], v[66:67]
	v_cvt_pk_bf16_f32 v64, v70, v71
	v_lshlrev_b64 v[70:71], 11, v[84:85]
	v_cvt_pk_bf16_f32 v65, v72, v73
	v_cvt_pk_bf16_f32 v66, v76, v77
	v_cvt_pk_bf16_f32 v67, v74, v75
	v_lshl_add_u64 v[68:69], v[68:69], 0, v[70:71]
	global_store_dwordx4 v[68:69], v[64:67], off nt
	s_cbranch_scc1 .LBB0_117
